# m7 plus: scan U/dl loads issued inside step 1 (code motion)
# speedup vs baseline: 1.0097x; 1.0097x over previous
.LBB0_870:
	ds_read_b128 v[108:111], v181
	ds_read_b128 v[112:115], v180 offset:62464
	ds_read_b128 v[116:119], v180 offset:62496
	ds_read_b128 v[214:217], v181 offset:32
	s_waitcnt lgkmcnt(2)
	v_mfma_f32_32x32x16_bf16 v[32:47], v[108:111], v[112:115], v[32:47]
	ds_read_b128 v[108:111], v181 offset:8704
	ds_read_b128 v[218:221], v181 offset:8736
	s_waitcnt lgkmcnt(1)
	v_mfma_f32_32x32x16_bf16 v[48:63], v[108:111], v[112:115], v[48:63]
	v_mfma_f32_32x32x16_bf16 v[32:47], v[214:217], v[116:119], v[32:47]
	s_waitcnt lgkmcnt(0)
	v_mfma_f32_32x32x16_bf16 v[48:63], v[218:221], v[116:119], v[48:63]
	ds_read_b128 v[108:111], v181 offset:64
	ds_read_b128 v[112:115], v180 offset:62528
	ds_read_b128 v[116:119], v180 offset:62560
	ds_read_b128 v[214:217], v181 offset:96
	s_cmpk_eq_i32 s47, 0x7c0
	s_cbranch_scc1 .LBB0_869
	s_and_saveexec_b64 s[52:53], s[10:11]
	s_cbranch_execz .LBB0_868
	v_add_u32_e32 v230, s47, v205
	v_mov_b64_e32 v[232:233], s[18:19]
	v_mad_i64_i32 v[232:233], s[34:35], v230, s60, v[232:233]
	v_lshl_add_u64 v[232:233], v[232:233], 0, s[36:37]
	v_lshl_add_u64 v[232:233], v[232:233], 0, v[124:125]
	v_lshlrev_b32_e32 v230, 1, v148
	v_mov_b32_e32 v231, v125
	v_lshl_add_u64 v[232:233], v[232:233], 0, v[230:231]
	v_lshl_add_u64 v[230:231], v[232:233], 0, s[38:39]
	v_add_co_u32_e32 v232, vcc, 0x1000, v232
	s_nop 1
	v_addc_co_u32_e32 v233, vcc, 0, v233, vcc
	global_load_dwordx2 v[132:133], v[230:231], off offset:64
	global_load_dwordx2 v[130:131], v[230:231], off offset:16
	global_load_dwordx2 v[134:135], v[230:231], off offset:32
	global_load_dwordx2 v[138:139], v[230:231], off offset:48
	global_load_dwordx2 v[136:137], v[232:233], off
	global_load_dwordx2 v[140:141], v[230:231], off offset:80
	global_load_dwordx2 v[142:143], v[230:231], off offset:96
	global_load_dwordx2 v[144:145], v[230:231], off offset:112

.Lmy_u_join:
	s_waitcnt lgkmcnt(2)
	v_mfma_f32_32x32x16_bf16 v[32:47], v[108:111], v[112:115], v[32:47]
	ds_read_b128 v[108:111], v181 offset:8768
	ds_read_b128 v[218:221], v181 offset:8800
	s_waitcnt lgkmcnt(1)
	v_mfma_f32_32x32x16_bf16 v[48:63], v[108:111], v[112:115], v[48:63]
	v_mfma_f32_32x32x16_bf16 v[32:47], v[214:217], v[116:119], v[32:47]
	s_waitcnt lgkmcnt(0)
	v_mfma_f32_32x32x16_bf16 v[48:63], v[218:221], v[116:119], v[48:63]
	ds_read_b128 v[108:111], v181 offset:128
	ds_read_b128 v[112:115], v180 offset:62592
	ds_read_b128 v[116:119], v180 offset:62624
	ds_read_b128 v[214:217], v181 offset:160
	s_waitcnt lgkmcnt(2)
	v_mfma_f32_32x32x16_bf16 v[32:47], v[108:111], v[112:115], v[32:47]
	ds_read_b128 v[108:111], v181 offset:8832
	ds_read_b128 v[218:221], v181 offset:8864
	s_waitcnt lgkmcnt(1)
	v_mfma_f32_32x32x16_bf16 v[48:63], v[108:111], v[112:115], v[48:63]
	v_mfma_f32_32x32x16_bf16 v[32:47], v[214:217], v[116:119], v[32:47]
	s_waitcnt lgkmcnt(0)
	v_mfma_f32_32x32x16_bf16 v[48:63], v[218:221], v[116:119], v[48:63]
	ds_read_b128 v[108:111], v181 offset:192
	ds_read_b128 v[112:115], v180 offset:62656
	ds_read_b128 v[116:119], v180 offset:62688
	ds_read_b128 v[214:217], v181 offset:224
	s_waitcnt lgkmcnt(2)
	v_mfma_f32_32x32x16_bf16 v[32:47], v[108:111], v[112:115], v[32:47]
	ds_read_b128 v[108:111], v181 offset:8896
	ds_read_b128 v[218:221], v181 offset:8928
	s_waitcnt lgkmcnt(1)
	v_mfma_f32_32x32x16_bf16 v[48:63], v[108:111], v[112:115], v[48:63]
	v_lshl_add_u64 v[112:113], v[168:169], 0, v[164:165]
	global_load_dwordx4 v[108:111], v[112:113], off
	s_nop 0
	global_load_dwordx4 v[112:115], v[112:113], off offset:-16
	v_mfma_f32_32x32x16_bf16 v[32:47], v[214:217], v[116:119], v[32:47]
	s_waitcnt lgkmcnt(0)
	v_mfma_f32_32x32x16_bf16 v[48:63], v[218:221], v[116:119], v[48:63]
	s_and_saveexec_b64 s[52:53], s[10:11]
	s_cbranch_execz .LBB0_872
	s_nop 7
	v_cvt_pk_bf16_f32 v116, v32, v33
	v_cvt_pk_bf16_f32 v117, v34, v35
	v_cvt_pk_bf16_f32 v122, v36, v37
	v_cvt_pk_bf16_f32 v123, v38, v39
	v_cvt_pk_bf16_f32 v118, v48, v49
	v_cvt_pk_bf16_f32 v119, v50, v51
	v_cvt_pk_bf16_f32 v208, v52, v53
	v_cvt_pk_bf16_f32 v209, v54, v55
	ds_write2_b64 v182, v[116:117], v[122:123] offset1:2
	ds_write2_b64 v182, v[118:119], v[208:209] offset0:8 offset1:10
	v_cvt_pk_bf16_f32 v116, v40, v41
	v_cvt_pk_bf16_f32 v117, v42, v43
	v_cvt_pk_bf16_f32 v122, v44, v45
	v_cvt_pk_bf16_f32 v123, v46, v47
	v_cvt_pk_bf16_f32 v118, v56, v57
	v_cvt_pk_bf16_f32 v119, v58, v59
	v_cvt_pk_bf16_f32 v208, v60, v61
	v_cvt_pk_bf16_f32 v209, v62, v63
	ds_write2_b64 v182, v[116:117], v[122:123] offset0:4 offset1:6
	ds_write2_b64 v182, v[118:119], v[208:209] offset0:12 offset1:14

	.amdhsa_kernel _Z4mega6Paramsii
		.amdhsa_group_segment_fixed_size 0
		.amdhsa_private_segment_fixed_size 0
		.amdhsa_kernarg_size 544
		.amdhsa_user_sgpr_count 2
		.amdhsa_user_sgpr_dispatch_ptr 0
		.amdhsa_user_sgpr_queue_ptr 0
		.amdhsa_user_sgpr_kernarg_segment_ptr 1
		.amdhsa_user_sgpr_dispatch_id 0
		.amdhsa_user_sgpr_kernarg_preload_length 0
		.amdhsa_user_sgpr_kernarg_preload_offset 0
		.amdhsa_user_sgpr_private_segment_size 0
		.amdhsa_uses_dynamic_stack 0
		.amdhsa_enable_private_segment 0
		.amdhsa_system_sgpr_workgroup_id_x 1
		.amdhsa_system_sgpr_workgroup_id_y 0
		.amdhsa_system_sgpr_workgroup_id_z 0
		.amdhsa_system_sgpr_workgroup_info 0
		.amdhsa_system_vgpr_workitem_id 2
		.amdhsa_next_free_vgpr 234
		.amdhsa_next_free_sgpr 102
		.amdhsa_accum_offset 236
		.amdhsa_reserve_vcc 1
		.amdhsa_float_round_mode_32 0
		.amdhsa_float_round_mode_16_64 0
		.amdhsa_float_denorm_mode_32 3
		.amdhsa_float_denorm_mode_16_64 3
		.amdhsa_dx10_clamp 1
		.amdhsa_ieee_mode 1
		.amdhsa_fp16_overflow 0
		.amdhsa_tg_split 0
		.amdhsa_exception_fp_ieee_invalid_op 0
		.amdhsa_exception_fp_denorm_src 0
		.amdhsa_exception_fp_ieee_div_zero 0
		.amdhsa_exception_fp_ieee_overflow 0
		.amdhsa_exception_fp_ieee_underflow 0
		.amdhsa_exception_fp_ieee_inexact 0
		.amdhsa_exception_int_div_zero 0
	.end_amdhsa_kernel

amdhsa.kernels:
  - .agpr_count:     0
    .args:
      - .offset:         0
        .size:           280
        .value_kind:     by_value
      - .offset:         280
        .size:           4
        .value_kind:     by_value
      - .offset:         284
        .size:           4
        .value_kind:     by_value
      - .offset:         288
        .size:           4
        .value_kind:     hidden_block_count_x
      - .offset:         292
        .size:           4
        .value_kind:     hidden_block_count_y
      - .offset:         296
        .size:           4
        .value_kind:     hidden_block_count_z
      - .offset:         300
        .size:           2
        .value_kind:     hidden_group_size_x
      - .offset:         302
        .size:           2
        .value_kind:     hidden_group_size_y
      - .offset:         304
        .size:           2
        .value_kind:     hidden_group_size_z
      - .offset:         306
        .size:           2
        .value_kind:     hidden_remainder_x
      - .offset:         308
        .size:           2
        .value_kind:     hidden_remainder_y
      - .offset:         310
        .size:           2
        .value_kind:     hidden_remainder_z
      - .offset:         328
        .size:           8
        .value_kind:     hidden_global_offset_x
      - .offset:         336
        .size:           8
        .value_kind:     hidden_global_offset_y
      - .offset:         344
        .size:           8
        .value_kind:     hidden_global_offset_z
      - .offset:         352
        .size:           2
        .value_kind:     hidden_grid_dims
      - .offset:         376
        .size:           8
        .value_kind:     hidden_multigrid_sync_arg
      - .offset:         408
        .size:           4
        .value_kind:     hidden_dynamic_lds_size
    .group_segment_fixed_size: 0
    .kernarg_segment_align: 8
    .kernarg_segment_size: 544
    .language:       OpenCL C
    .language_version:
      - 2
      - 0
    .max_flat_workgroup_size: 512
    .name:           _Z4mega6Paramsii
    .private_segment_fixed_size: 0
    .sgpr_count:     108
    .sgpr_spill_count: 8
    .symbol:         _Z4mega6Paramsii.kd
    .uniform_work_group_size: 1
    .uses_dynamic_stack: false
    .vgpr_count:     234
    .vgpr_spill_count: 0
    .wavefront_size: 64
